# v095 + P5 out_gate slice loaded once (4 reloads and the waits that drained the y_b stores removed per row)
# speedup vs baseline: 1.0038x; 1.0038x over previous
; __device__ __forceinline__ float bf_lo(unsigned u) { return __uint_as_float(u << 16); }
; __device__ __forceinline__ float bf_hi(unsigned u) { return __uint_as_float(u & 0xffff0000u); }
; __device__ __forceinline__ unsigned pk2(float lo, float hi) { return pg8::cvt_pk_bf16(lo, hi); }
; __global__ void __launch_bounds__(NT, 2) mk_fwd(Args args) {
;     ...
;         for (int t_ = gw; t_ < MTOK * RMUL(5); t_ += NGW) { const int t = t_ & (MTOK - 1);
;             const size_t o = (size_t)t * 1024 + lane * 16;
;             f32x4 y[4];
; #pragma unroll
;             for (int j = 0; j < 4; ++j) y[j] = *(const f32x4*)(Y + o + 4 * j);
;             float s = 0.f;
; #pragma unroll
;             for (int j = 0; j < 4; ++j) s += (y[j].x + y[j].y) + (y[j].z + y[j].w);
;             s = quad_sum(s); const float mean = s * (1.0f / 64.0f);
;             float s2 = 0.f;
; #pragma unroll
;             for (int j = 0; j < 4; ++j) { y[j] = y[j] - mean; s2 += (y[j].x * y[j].x + y[j].y * y[j].y) + (y[j].z * y[j].z + y[j].w * y[j].w); }
;             s2 = quad_sum(s2); const float rstd = rsqrtf(s2 * (1.0f / 64.0f) + 64e-5f);
;             u32x4 r8[2], k8[2], v8[2], g8[2];
; #pragma unroll
;             for (int j = 0; j < 2; ++j) { r8[j] = *(const u32x4*)(RR + o + 8 * j); k8[j] = *(const u32x4*)(KP + o + 8 * j); v8[j] = *(const u32x4*)(VV + o + 8 * j); g8[j] = *(const u32x4*)(GG + o + 8 * j); }
;             float dp = 0.f;
; #pragma unroll
;             for (int j = 0; j < 2; ++j)
; #pragma unroll
;                 for (int e = 0; e < 4; ++e) { const int col = lane * 16 + j * 8 + e * 2; dp += bf_lo(r8[j][e]) * bf_lo(k8[j][e]) * rk[col] + bf_hi(r8[j][e]) * bf_hi(k8[j][e]) * rk[col + 1]; }
;             dp = quad_sum(dp);
;             u32x4 ov[2];
; #pragma unroll
;             for (int j = 0; j < 2; ++j)
; #pragma unroll
;                 for (int e = 0; e < 4; ++e) { const int c = j * 8 + e * 2; const int col = lane * 16 + c;
;                     const float y0 = y[c >> 2][c & 3], y1 = y[(c + 1) >> 2][(c + 1) & 3];
;                     const float o0 = (y0 * rstd * lng[col] + lnb[col] + dp * bf_lo(v8[j][e])) * bf_lo(g8[j][e]);
;                     const float o1 = (y1 * rstd * lng[col + 1] + lnb[col + 1] + dp * bf_hi(v8[j][e])) * bf_hi(g8[j][e]);
;                     ov[j][e] = pk2(o0, o1); }
;             bf16* op = HB + (size_t)t * DM + 1024 + lane * 16;
.LBB0_506:
	s_cmp_lt_i32 s94, 6
	s_cselect_b64 s[0:1], -1, 0
	s_and_b64 s[0:1], s[0:1], s[6:7]
	s_and_b64 s[6:7], s[0:1], s[86:87]
	s_andn2_b64 vcc, exec, s[6:7]
	v_lshlrev_b32_e32 v136, 6, v128
	v_lshlrev_b32_e32 v138, 5, v128
	s_cbranch_vccnz .LBB0_509
	v_readlane_b32 s40, v249, 8
	v_readlane_b32 s48, v249, 16
	v_readlane_b32 s49, v249, 17
	v_mov_b32_e32 v137, 0
	v_readlane_b32 s46, v249, 14
	v_readlane_b32 s47, v249, 15
	v_readlane_b32 s50, v249, 18
	v_readlane_b32 s51, v249, 19
	s_mov_b64 s[8:9], s[48:49]
	v_mbcnt_hi_u32_b32 v61, -1, v169
	s_mov_b64 s[10:11], s[50:51]
	s_mov_b64 s[6:7], s[46:47]
	v_mov_b32_e32 v139, v137
	s_waitcnt vmcnt(0)
	v_and_b32_e32 v0, 64, v61
	v_lshl_add_u64 v[48:49], s[6:7], 0, v[136:137]
	v_lshl_add_u64 v[50:51], s[8:9], 0, v[136:137]
	v_lshl_add_u64 v[52:53], s[10:11], 0, v[136:137]
	v_lshl_add_u64 v[54:55], s[56:57], 0, v[136:137]
	v_lshl_add_u64 v[56:57], s[80:81], 0, v[138:139]
	s_mov_b32 s7, 0
	v_mov_b32_e32 v60, 0x3a27c5ac
	s_mov_b32 s3, 0x800000
	v_xor_b32_e32 v62, 16, v61
	v_add_u32_e32 v63, 64, v0
	v_xor_b32_e32 v64, 32, v61
	v_mov_b32_e32 v65, 0x358637bd
	s_mov_b32 s8, s70
	v_readlane_b32 s41, v249, 9
	v_readlane_b32 s42, v249, 10
	v_readlane_b32 s43, v249, 11
	v_readlane_b32 s44, v249, 12
	v_readlane_b32 s45, v249, 13
	v_readlane_b32 s52, v249, 20
	v_readlane_b32 s53, v249, 21
	v_readlane_b32 s54, v249, 22
	v_readlane_b32 s55, v249, 23
	global_load_dwordx4 v[200:203], v[54:55], off
	global_load_dwordx4 v[204:207], v[54:55], off offset:16
	global_load_dwordx4 v[208:211], v[54:55], off offset:32
	global_load_dwordx4 v[212:215], v[54:55], off offset:48
	s_waitcnt vmcnt(0)
.LBB0_508:
	s_and_b32 s6, s8, 0x3fff
	v_cmp_lt_i32_e32 vcc, v62, v63
	v_lshl_or_b32 v66, s6, 10, v130
	s_lshl_b32 s6, s6, 12
	v_cndmask_b32_e32 v58, v61, v62, vcc
	v_cmp_lt_i32_e32 vcc, v64, v63
	v_lshlrev_b32_e32 v114, 2, v66
	v_lshlrev_b32_e32 v115, 1, v66
	v_cndmask_b32_e32 v59, v61, v64, vcc
	global_load_dwordx4 v[0:3], v[48:49], off offset:48
	global_load_dwordx4 v[4:7], v[48:49], off offset:32
	global_load_dwordx4 v[8:11], v[48:49], off offset:16
	global_load_dwordx4 v[12:15], v[48:49], off
	global_load_dwordx4 v[16:19], v[50:51], off
	global_load_dwordx4 v[28:31], v[50:51], off offset:16
	global_load_dwordx4 v[20:23], v[52:53], off
	global_load_dwordx4 v[24:27], v[52:53], off offset:16
	global_load_dwordx4 v[36:39], v[50:51], off offset:32
	global_load_dwordx4 v[40:43], v[50:51], off offset:48
	global_load_dwordx4 v[44:47], v[52:53], off offset:32
	global_load_dwordx4 v[32:35], v[52:53], off offset:48
	v_lshlrev_b32_e32 v129, 2, v58
	v_lshlrev_b32_e32 v131, 2, v59
	v_lshl_add_u64 v[58:59], v[56:57], 0, s[6:7]
	global_load_dwordx4 v[66:69], v114, s[20:21]
	global_load_dwordx4 v[70:73], v114, s[20:21] offset:16
	global_load_dwordx4 v[74:77], v114, s[20:21] offset:32
	global_load_dwordx4 v[78:81], v114, s[20:21] offset:48
	global_load_dwordx4 v[82:85], v115, s[28:29]
	global_load_dwordx4 v[86:89], v115, s[96:97]
	global_load_dwordx4 v[90:93], v115, s[28:29] offset:16
	global_load_dwordx4 v[94:97], v115, s[96:97] offset:16
	global_load_dwordx4 v[98:101], v115, s[24:25]
	global_load_dwordx4 v[102:105], v115, s[26:27]
	global_load_dwordx4 v[106:109], v115, s[24:25] offset:16
	global_load_dwordx4 v[110:113], v115, s[26:27] offset:16
	s_nop 0
	global_load_dwordx4 v[114:117], v[58:59], off offset:16
	global_load_dwordx4 v[118:121], v[58:59], off
	s_add_i32 s8, s8, s72
	s_cmpk_lt_i32 s8, 0x4000
	s_waitcnt vmcnt(13)
	v_mov_b32_e32 v142, v66
	v_mov_b32_e32 v143, v69
	s_waitcnt vmcnt(12)
	v_mov_b32_e32 v144, v71
	v_mov_b32_e32 v122, v13
	v_mov_b32_e32 v123, v14
	v_mov_b32_e32 v13, v15
	v_mov_b32_e32 v14, v67
	v_mov_b32_e32 v15, v68
	v_mov_b32_e32 v145, v72
	v_mov_b32_e32 v146, v70
	v_mov_b32_e32 v147, v73
	v_mov_b32_e32 v140, v1
	v_mov_b32_e32 v1, v3
	s_waitcnt vmcnt(9)
	v_and_b32_e32 v154, 0xffff0000, v82
	v_lshlrev_b32_e32 v155, 16, v83
	s_waitcnt vmcnt(8)
	v_and_b32_e32 v156, 0xffff0000, v86
	v_lshlrev_b32_e32 v157, 16, v87
	v_lshlrev_b32_e32 v82, 16, v82
	v_and_b32_e32 v83, 0xffff0000, v83
	v_lshlrev_b32_e32 v86, 16, v86
	v_and_b32_e32 v87, 0xffff0000, v87
	s_waitcnt vmcnt(5)
	v_lshlrev_b32_e32 v137, 16, v99
	v_and_b32_e32 v172, 0xffff0000, v99
	s_waitcnt vmcnt(3)
	v_lshlrev_b32_e32 v190, 16, v108
	v_and_b32_e32 v192, 0xffff0000, v108
	v_lshlrev_b32_e32 v99, 16, v109
	v_and_b32_e32 v3, 0xffff0000, v109
	v_pk_add_f32 v[14:15], v[14:15], v[142:143]
	v_pk_add_f32 v[108:109], v[144:145], v[146:147]
	v_mov_b32_e32 v126, v5
	v_mov_b32_e32 v5, v7
	v_pk_mul_f32 v[82:83], v[82:83], v[86:87]
	v_add_f32_e32 v7, v14, v15
	v_pk_add_f32 v[14:15], v[108:109], v[108:109] op_sel:[0,1] op_sel_hi:[1,0]
	v_add_f32_e32 v148, v74, v75
	v_add_f32_e32 v150, v76, v77
	v_mov_b32_e32 v153, v78
	v_mov_b32_e32 v149, v80
	v_mov_b32_e32 v151, v81
	v_and_b32_e32 v158, 0xffff0000, v84
	v_lshlrev_b32_e32 v159, 16, v85
	v_and_b32_e32 v160, 0xffff0000, v88
	v_lshlrev_b32_e32 v161, 16, v89
	v_lshlrev_b32_e32 v84, 16, v84
	v_and_b32_e32 v85, 0xffff0000, v85
	v_lshlrev_b32_e32 v88, 16, v88
	v_and_b32_e32 v89, 0xffff0000, v89
	s_waitcnt vmcnt(2)
; __device__ __forceinline__ float bf_lo(unsigned u) { return __uint_as_float(u << 16); }
; __device__ __forceinline__ float bf_hi(unsigned u) { return __uint_as_float(u & 0xffff0000u); }
; __device__ __forceinline__ unsigned pk2(float lo, float hi) { return pg8::cvt_pk_bf16(lo, hi); }
; __device__ __forceinline__ float quad_sum(float v) { v += dpp_mov<0xB1>(v); v += dpp_mov<0x4E>(v); return v; }
; __global__ void __launch_bounds__(NT, 2) mk_fwd(Args args) {
;     ...
;             for (int j = 0; j < 4; ++j) y[j] = *(const f32x4*)(Y + o + 4 * j);
;             float s = 0.f;
; #pragma unroll
;             for (int j = 0; j < 4; ++j) s += (y[j].x + y[j].y) + (y[j].z + y[j].w);
;             s = quad_sum(s); const float mean = s * (1.0f / 64.0f);
;             float s2 = 0.f;
; #pragma unroll
;             for (int j = 0; j < 4; ++j) { y[j] = y[j] - mean; s2 += (y[j].x * y[j].x + y[j].y * y[j].y) + (y[j].z * y[j].z + y[j].w * y[j].w); }
;             s2 = quad_sum(s2); const float rstd = rsqrtf(s2 * (1.0f / 64.0f) + 64e-5f);
;             u32x4 r8[2], k8[2], v8[2], g8[2];
; #pragma unroll
;             for (int j = 0; j < 2; ++j) { r8[j] = *(const u32x4*)(RR + o + 8 * j); k8[j] = *(const u32x4*)(KP + o + 8 * j); v8[j] = *(const u32x4*)(VV + o + 8 * j); g8[j] = *(const u32x4*)(GG + o + 8 * j); }
;             float dp = 0.f;
; #pragma unroll
;             for (int j = 0; j < 2; ++j)
; #pragma unroll
;                 for (int e = 0; e < 4; ++e) { const int col = lane * 16 + j * 8 + e * 2; dp += bf_lo(r8[j][e]) * bf_lo(k8[j][e]) * rk[col] + bf_hi(r8[j][e]) * bf_hi(k8[j][e]) * rk[col + 1]; }
;             dp = quad_sum(dp);
;             u32x4 ov[2];
; #pragma unroll
;             for (int j = 0; j < 2; ++j)
; #pragma unroll
;                 for (int e = 0; e < 4; ++e) { const int c = j * 8 + e * 2; const int col = lane * 16 + c;
;                     const float y0 = y[c >> 2][c & 3], y1 = y[(c + 1) >> 2][(c + 1) & 3];
;                     const float o0 = (y0 * rstd * lng[col] + lnb[col] + dp * bf_lo(v8[j][e])) * bf_lo(g8[j][e]);
;                     const float o1 = (y1 * rstd * lng[col + 1] + lnb[col + 1] + dp * bf_hi(v8[j][e])) * bf_hi(g8[j][e]);
;                     ov[j][e] = pk2(o0, o1); }
	v_lshlrev_b32_e32 v191, 16, v112
	v_and_b32_e32 v193, 0xffff0000, v112
	v_lshlrev_b32_e32 v194, 16, v113
	v_and_b32_e32 v195, 0xffff0000, v113
	v_pk_mul_f32 v[112:113], v[154:155], v[156:157]
	v_pk_mul_f32 v[12:13], v[12:13], v[82:83]
	v_add_f32_e32 v152, 0, v7
	v_mov_b32_e32 v15, v79
	v_mov_b32_e32 v124, v9
	v_mov_b32_e32 v9, v11
	v_lshlrev_b32_e32 v183, 16, v110
	v_and_b32_e32 v185, 0xffff0000, v110
	v_lshlrev_b32_e32 v187, 16, v111
	v_and_b32_e32 v189, 0xffff0000, v111
	v_pk_add_f32 v[110:111], v[148:149], v[150:151]
	v_pk_mul_f32 v[84:85], v[84:85], v[88:89]
	v_pk_fma_f32 v[12:13], v[122:123], v[112:113], v[12:13]
	v_pk_add_f32 v[14:15], v[152:153], v[14:15]
	v_mov_b32_e32 v125, v10
	v_and_b32_e32 v162, 0xffff0000, v90
	v_lshlrev_b32_e32 v163, 16, v91
	v_and_b32_e32 v164, 0xffff0000, v94
	v_lshlrev_b32_e32 v165, 16, v95
	v_lshlrev_b32_e32 v90, 16, v90
	v_and_b32_e32 v91, 0xffff0000, v91
	v_lshlrev_b32_e32 v94, 16, v94
	v_and_b32_e32 v95, 0xffff0000, v95
	v_pk_mul_f32 v[86:87], v[158:159], v[160:161]
	v_pk_mul_f32 v[8:9], v[8:9], v[84:85]
	v_add_f32_e32 v7, 0, v12
	v_pk_add_f32 v[14:15], v[14:15], v[110:111]
	v_pk_mul_f32 v[90:91], v[90:91], v[94:95]
	v_pk_fma_f32 v[8:9], v[124:125], v[86:87], v[8:9]
	v_add_f32_e32 v7, v7, v13
	v_add_f32_e32 v12, v14, v15
	v_mov_b32_e32 v127, v6
	v_and_b32_e32 v166, 0xffff0000, v92
	v_lshlrev_b32_e32 v167, 16, v93
	v_and_b32_e32 v170, 0xffff0000, v96
	v_lshlrev_b32_e32 v171, 16, v97
	v_lshlrev_b32_e32 v92, 16, v92
	v_and_b32_e32 v93, 0xffff0000, v93
	v_lshlrev_b32_e32 v96, 16, v96
	v_and_b32_e32 v97, 0xffff0000, v97
	v_pk_mul_f32 v[88:89], v[162:163], v[164:165]
	v_pk_mul_f32 v[4:5], v[4:5], v[90:91]
	v_add_f32_e32 v7, v7, v8
	v_add_f32_dpp v8, v12, v12 quad_perm:[1,0,3,2] row_mask:0xf bank_mask:0xf bound_ctrl:1
	v_mov_b32_e32 v10, v17
	v_pk_mul_f32 v[92:93], v[92:93], v[96:97]
	v_pk_fma_f32 v[4:5], v[126:127], v[88:89], v[4:5]
	v_add_f32_e32 v7, v7, v9
	v_add_f32_dpp v17, v8, v8 quad_perm:[2,3,0,1] row_mask:0xf bank_mask:0xf bound_ctrl:1
	v_mov_b32_e32 v141, v2
	v_pk_mul_f32 v[94:95], v[166:167], v[170:171]
	v_pk_mul_f32 v[0:1], v[0:1], v[92:93]
	v_add_f32_e32 v4, v7, v4
	v_fmamk_f32 v9, v17, 0xbc800000, v67
	v_fmamk_f32 v8, v17, 0xbc800000, v66
	v_fmamk_f32 v69, v17, 0xbc800000, v69
	v_fmac_f32_e32 v68, 0xbc800000, v17
	v_fmamk_f32 v13, v17, 0xbc800000, v71
	v_fmamk_f32 v12, v17, 0xbc800000, v70
	v_fmamk_f32 v73, v17, 0xbc800000, v73
	v_fmac_f32_e32 v72, 0xbc800000, v17
	v_pk_fma_f32 v[0:1], v[140:141], v[94:95], v[0:1]
	v_fmamk_f32 v15, v17, 0xbc800000, v75
	v_fmamk_f32 v14, v17, 0xbc800000, v74
	v_add_f32_e32 v7, v4, v5
	v_pk_mul_f32 v[4:5], v[68:69], v[68:69]
	v_pk_mul_f32 v[66:67], v[8:9], v[8:9]
	v_pk_mul_f32 v[70:71], v[72:73], v[72:73]
	v_pk_mul_f32 v[74:75], v[12:13], v[12:13]
	v_fmamk_f32 v77, v17, 0xbc800000, v77
	v_add_f32_e32 v0, v7, v0
	v_pk_mov_b32 v[82:83], v[66:67], v[4:5] op_sel:[1,0]
	v_mov_b32_e32 v67, v5
	v_pk_mov_b32 v[4:5], v[74:75], v[70:71] op_sel:[1,0]
	v_mov_b32_e32 v75, v71
	v_mov_b32_e32 v6, v20
	v_fmac_f32_e32 v76, 0xbc800000, v17
	v_fmamk_f32 v84, v17, 0xbc800000, v81
	v_fmamk_f32 v85, v17, 0xbc800000, v80
	v_fmamk_f32 v79, v17, 0xbc800000, v79
	v_fmac_f32_e32 v78, 0xbc800000, v17
	v_mul_f32_e32 v20, v15, v15
	v_mul_f32_e32 v80, v77, v77
	v_add_f32_e32 v7, v0, v1
	v_pk_add_f32 v[0:1], v[82:83], v[66:67]
	v_pk_add_f32 v[4:5], v[4:5], v[74:75]
	v_mul_f32_e32 v86, v78, v78
	v_mul_f32_e32 v87, v79, v79
	v_mul_f32_e32 v17, v85, v85
	v_mul_f32_e32 v88, v84, v84
	v_pk_fma_f32 v[70:71], v[14:15], v[14:15], v[20:21] op_sel_hi:[1,1,0]
	v_pk_fma_f32 v[80:81], v[76:77], v[76:77], v[80:81] op_sel_hi:[1,1,0]
	v_pk_add_f32 v[0:1], v[0:1], v[0:1] op_sel:[0,1] op_sel_hi:[1,0]
	v_pk_add_f32 v[4:5], v[4:5], v[4:5] op_sel:[0,1] op_sel_hi:[1,0]
	v_mov_b32_e32 v71, v17
	v_mov_b32_e32 v81, v88
	v_mov_b32_e32 v1, v86
	v_mov_b32_e32 v5, v87
	v_pk_add_f32 v[66:67], v[70:71], v[80:81]
	v_pk_add_f32 v[0:1], v[0:1], v[4:5]
	v_add_f32_dpp v17, v7, v7 quad_perm:[1,0,3,2] row_mask:0xf bank_mask:0xf bound_ctrl:1
	v_pk_add_f32 v[0:1], v[0:1], v[66:67]
	v_mov_b32_e32 v2, v43
	v_add_f32_e32 v0, v0, v1
	v_mov_b32_dpp v7, v17 quad_perm:[2,3,0,1] row_mask:0xf bank_mask:0xf bound_ctrl:1
	v_lshlrev_b32_e32 v43, 16, v98
	v_add_f32_dpp v0, v0, v0 quad_perm:[1,0,3,2] row_mask:0xf bank_mask:0xf bound_ctrl:1
	v_and_b32_e32 v176, 0xffff0000, v100
	v_lshlrev_b32_e32 v178, 16, v101
	v_add_f32_dpp v0, v0, v0 quad_perm:[2,3,0,1] row_mask:0xf bank_mask:0xf bound_ctrl:1
	v_fmamk_f32 v0, v0, 0x3c800000, v60
	v_mul_f32_e32 v1, 0x4b800000, v0
	v_cmp_gt_f32_e32 vcc, s3, v0
	v_lshlrev_b32_e32 v182, 16, v106
	v_lshlrev_b32_e32 v133, 16, v102
	v_cndmask_b32_e32 v0, v0, v1, vcc
	v_rsq_f32_e32 v0, v0
	v_and_b32_e32 v11, 0xffff0000, v98
	v_lshlrev_b32_e32 v139, 16, v103
	v_and_b32_e32 v173, 0xffff0000, v103
	v_mul_f32_e32 v1, 0x45800000, v0
	v_cndmask_b32_e32 v4, v0, v1, vcc
	v_mul_f32_e32 v0, v4, v8
	v_mul_f32_e32 v1, v4, v68
	v_mul_f32_e32 v5, v4, v69
	v_mul_f32_e32 v8, v4, v12
	v_mul_f32_e32 v12, v4, v13
	v_mul_f32_e32 v13, v4, v72
	v_mul_f32_e32 v14, v4, v14
	v_mul_f32_e32 v16, v16, v0
	v_mul_f32_e32 v20, v4, v73
	v_mul_f32_e32 v15, v4, v15
	v_fma_f32 v18, v18, v1, v22
	v_fmac_f32_e32 v23, v5, v19
	v_fma_f32 v5, v28, v8, v24
	v_fma_f32 v8, v12, v29, v25
	v_fma_f32 v12, v30, v13, v26
	v_fma_f32 v13, v36, v14, v44
	v_pk_add_f32 v[0:1], v[6:7], v[16:17]
	v_lshlrev_b32_e32 v174, 16, v100
	v_and_b32_e32 v177, 0xffff0000, v104
	v_lshlrev_b32_e32 v179, 16, v105
	v_and_b32_e32 v180, 0xffff0000, v101
	v_and_b32_e32 v184, 0xffff0000, v106
	v_fmac_f32_e32 v27, v20, v31
	v_fma_f32 v14, v15, v37, v45
	v_fma_f32 v6, v1, v43, v0
; __device__ __forceinline__ float bf_lo(unsigned u) { return __uint_as_float(u << 16); }
; __device__ __forceinline__ float bf_hi(unsigned u) { return __uint_as_float(u & 0xffff0000u); }
; __device__ __forceinline__ unsigned pk2(float lo, float hi) { return pg8::cvt_pk_bf16(lo, hi); }
; __device__ __forceinline__ float wave_sum(float v) { v = row16_sum(v); v += __shfl_xor(v, 16); v += __shfl_xor(v, 32); return v; }
; __global__ void __launch_bounds__(NT, 2) mk_fwd(Args args) {
;     ...
;             bf16* op = HB + (size_t)t * DM + 1024 + lane * 16;
;             *(u32x4*)op = ov[0]; *(u32x4*)(op + 8) = ov[1];
;             {
;                 bf16* ap = HB + (size_t)t * DM + lane * 16; u32x4 ya[2]; ya[0] = *(const u32x4*)ap; ya[1] = *(const u32x4*)(ap + 8);
;                 float q2 = 0.f;
; #pragma unroll
;                 for (int j = 0; j < 2; ++j)
; #pragma unroll
;                     for (int e = 0; e < 4; ++e) { const float v0 = bf_lo(ya[j][e]), v1 = bf_hi(ya[j][e]); q2 += v0 * v0 + v1 * v1; }
;                 q2 = wave_sum(q2);
;                 const float ri = rsqrtf(q2 * (1.0f / 1024.0f) + 1e-6f);
; #pragma unroll
;                 for (int j = 0; j < 2; ++j)
; #pragma unroll
;                     for (int e = 0; e < 4; ++e) { const int col = lane * 16 + j * 8 + e * 2; ya[j][e] = pk2(bf_lo(ya[j][e]) * ri * og[col], bf_hi(ya[j][e]) * ri * og[col + 1]); }
;                 *(u32x4*)ap = ya[0]; *(u32x4*)(ap + 8) = ya[1];
;             }
;         }
	v_mul_f32_e32 v0, v4, v9
	v_fmac_f32_e32 v18, v1, v137
	v_fmac_f32_e32 v23, v1, v172
	v_fmac_f32_e32 v8, v1, v176
	v_fmac_f32_e32 v12, v1, v178
	v_fmac_f32_e32 v13, v1, v182
	v_lshlrev_b32_e32 v175, 16, v104
	v_and_b32_e32 v181, 0xffff0000, v105
	v_mul_f32_e32 v66, v4, v76
	v_mul_f32_e32 v67, v4, v77
	v_mul_f32_e32 v68, v4, v78
	v_mul_f32_e32 v69, v4, v79
	v_mul_f32_e32 v98, v4, v85
	v_fmac_f32_e32 v5, v1, v174
	v_fmac_f32_e32 v27, v1, v180
	v_fmac_f32_e32 v14, v1, v184
	v_mul_f32_e32 v16, v6, v133
	v_pk_mul_f32 v[10:11], v[0:1], v[10:11]
	v_mul_f32_e32 v6, v18, v139
	v_mul_f32_e32 v7, v23, v173
	v_mul_f32_e32 v8, v8, v177
	v_mul_f32_e32 v12, v12, v179
	v_mul_f32_e32 v13, v13, v183
	v_mov_b32_e32 v0, v42
	v_lshlrev_b32_e32 v186, 16, v107
	v_and_b32_e32 v188, 0xffff0000, v107
	v_fma_f32 v15, v38, v66, v46
	v_fmac_f32_e32 v47, v67, v39
	v_fma_f32 v19, v40, v68, v32
	v_fma_f32 v20, v69, v41, v33
	v_mul_f32_e32 v9, v5, v175
	v_mul_f32_e32 v17, v27, v181
	v_mul_f32_e32 v14, v14, v185
	v_cvt_pk_bf16_f32 v5, v6, v7
	v_cvt_pk_bf16_f32 v6, v9, v8
	v_cvt_pk_bf16_f32 v7, v12, v17
	v_cvt_pk_bf16_f32 v8, v13, v14
	v_pk_mul_f32 v[12:13], v[0:1], v[98:99]
	v_mul_f32_e32 v0, v4, v84
	v_fmac_f32_e32 v15, v1, v186
	v_fmac_f32_e32 v47, v1, v188
	v_fmac_f32_e32 v19, v1, v190
	v_fmac_f32_e32 v20, v1, v192
	v_add_f32_e32 v21, v10, v21
	v_pk_mul_f32 v[0:1], v[0:1], v[2:3]
	v_and_b32_e32 v135, 0xffff0000, v102
	v_add_f32_e32 v4, v21, v11
	v_add_f32_e32 v11, v34, v12
	v_add_f32_e32 v0, v0, v35
	v_mul_f32_e32 v2, v4, v135
	v_add_f32_e32 v3, v11, v13
	v_add_f32_e32 v0, v0, v1
	v_mul_f32_e32 v15, v15, v187
	v_mul_f32_e32 v18, v47, v189
	v_mul_f32_e32 v19, v19, v191
	v_mul_f32_e32 v20, v20, v193
	v_cvt_pk_bf16_f32 v9, v15, v18
	v_cvt_pk_bf16_f32 v10, v19, v20
	v_cvt_pk_bf16_f32 v4, v16, v2
	v_mul_f32_e32 v2, v3, v194
	v_mul_f32_e32 v0, v0, v195
	global_store_dwordx4 v[58:59], v[4:7], off offset:2048
	v_cvt_pk_bf16_f32 v11, v2, v0
	global_store_dwordx4 v[58:59], v[8:11], off offset:2064
	v_mov_b32_e32 v0, v200
	v_mov_b32_e32 v1, v201
	v_mov_b32_e32 v2, v202
	v_mov_b32_e32 v3, v203
	v_mov_b32_e32 v4, v204
	v_mov_b32_e32 v5, v205
	v_mov_b32_e32 v6, v206
	v_mov_b32_e32 v7, v207
	s_nop 0
	v_mov_b32_e32 v8, v208
	v_mov_b32_e32 v9, v209
	v_mov_b32_e32 v10, v210
	v_mov_b32_e32 v11, v211
	v_mov_b32_e32 v12, v212
	v_mov_b32_e32 v13, v213
	v_mov_b32_e32 v14, v214
	v_mov_b32_e32 v15, v215
	s_waitcnt vmcnt(2)
	v_lshlrev_b32_e32 v196, 16, v118
	v_and_b32_e32 v118, 0xffff0000, v118
	v_lshlrev_b32_e32 v197, 16, v119
	v_and_b32_e32 v119, 0xffff0000, v119
	v_lshlrev_b32_e32 v198, 16, v120
	v_and_b32_e32 v120, 0xffff0000, v120
	v_lshlrev_b32_e32 v100, 16, v114
	v_lshlrev_b32_e32 v101, 16, v115
	v_and_b32_e32 v103, 0xffff0000, v115
	v_and_b32_e32 v102, 0xffff0000, v114
	v_mul_f32_e32 v114, v118, v118
	v_mul_f32_e32 v115, v119, v119
	v_lshlrev_b32_e32 v199, 16, v121
	v_and_b32_e32 v121, 0xffff0000, v121
	v_lshlrev_b32_e32 v104, 16, v116
	v_and_b32_e32 v106, 0xffff0000, v116
	v_mul_f32_e32 v116, v120, v120
	v_fmac_f32_e32 v114, v196, v196
	v_fmac_f32_e32 v115, v197, v197
	v_lshlrev_b32_e32 v105, 16, v117
	v_and_b32_e32 v107, 0xffff0000, v117
	v_mul_f32_e32 v117, v121, v121
	v_fmac_f32_e32 v116, v198, v198
	v_add_f32_e32 v20, v114, v115
	v_pk_mul_f32 v[96:97], v[102:103], v[102:103]
	v_fmac_f32_e32 v117, v199, v199
	v_add_f32_e32 v20, v20, v116
	v_pk_fma_f32 v[18:19], v[100:101], v[100:101], v[96:97]
	v_add_f32_e32 v20, v20, v117
	v_pk_mul_f32 v[16:17], v[106:107], v[106:107]
	v_add_f32_e32 v18, v20, v18
	v_pk_fma_f32 v[16:17], v[104:105], v[104:105], v[16:17]
	v_add_f32_e32 v18, v18, v19
	v_add_f32_e32 v16, v18, v16
	v_add_f32_e32 v16, v16, v17
	s_nop 1
	v_add_f32_dpp v16, v16, v16 quad_perm:[1,0,3,2] row_mask:0xf bank_mask:0xf bound_ctrl:1
	s_nop 1
	v_add_f32_dpp v16, v16, v16 quad_perm:[2,3,0,1] row_mask:0xf bank_mask:0xf bound_ctrl:1
	s_nop 1
	v_add_f32_dpp v16, v16, v16 row_half_mirror row_mask:0xf bank_mask:0xf bound_ctrl:1
	s_nop 1
	v_add_f32_dpp v16, v16, v16 row_mirror row_mask:0xf bank_mask:0xf bound_ctrl:1
	ds_bpermute_b32 v17, v129, v16
	s_waitcnt lgkmcnt(0)
	v_add_f32_e32 v16, v16, v17
	ds_bpermute_b32 v17, v131, v16
	s_waitcnt lgkmcnt(0)
	v_add_f32_e32 v16, v16, v17
	v_fmamk_f32 v16, v16, 0x3a800000, v65
	v_mul_f32_e32 v17, 0x4b800000, v16
	v_cmp_gt_f32_e32 vcc, s3, v16
	s_nop 1
	v_cndmask_b32_e32 v16, v16, v17, vcc
	v_rsq_f32_e32 v16, v16
	s_nop 0
	v_mul_f32_e32 v17, 0x45800000, v16
	v_cndmask_b32_e32 v16, v16, v17, vcc
	v_mul_f32_e32 v17, v16, v196
	v_mul_f32_e32 v18, v16, v118
	v_mul_f32_e32 v19, v16, v197
	v_mul_f32_e32 v20, v16, v119
	v_mul_f32_e32 v21, v16, v198
	v_mul_f32_e32 v22, v16, v120
	v_mul_f32_e32 v23, v16, v199
	v_mul_f32_e32 v24, v16, v121
	v_mul_f32_e32 v0, v0, v17
	v_mul_f32_e32 v1, v1, v18
	v_mul_f32_e32 v2, v2, v19
	v_mul_f32_e32 v3, v3, v20
	v_mul_f32_e32 v25, v16, v100
	v_mul_f32_e32 v26, v16, v102
	v_mul_f32_e32 v27, v16, v101
	v_mul_f32_e32 v28, v16, v103
	v_mul_f32_e32 v29, v16, v104
	v_mul_f32_e32 v30, v16, v106
	v_mul_f32_e32 v31, v16, v105
	v_mul_f32_e32 v16, v16, v107
	v_mul_f32_e32 v4, v4, v21
	v_mul_f32_e32 v5, v5, v22
	v_mul_f32_e32 v6, v6, v23
	v_mul_f32_e32 v7, v7, v24
	v_cvt_pk_bf16_f32 v0, v0, v1
	v_cvt_pk_bf16_f32 v1, v2, v3
	v_cvt_pk_bf16_f32 v2, v4, v5
	v_cvt_pk_bf16_f32 v3, v6, v7
	v_mul_f32_e32 v8, v8, v25
	v_mul_f32_e32 v9, v9, v26
	v_mul_f32_e32 v10, v10, v27
	v_mul_f32_e32 v11, v11, v28
	v_mul_f32_e32 v12, v12, v29
	v_mul_f32_e32 v13, v13, v30
	v_mul_f32_e32 v14, v14, v31
	v_mul_f32_e32 v15, v15, v16
	v_cvt_pk_bf16_f32 v4, v8, v9
	v_cvt_pk_bf16_f32 v5, v10, v11
	v_cvt_pk_bf16_f32 v6, v12, v13
	v_cvt_pk_bf16_f32 v7, v14, v15
	global_store_dwordx4 v[58:59], v[0:3], off
	global_store_dwordx4 v[58:59], v[4:7], off offset:16
	s_cbranch_scc1 .LBB0_508

; __device__ __forceinline__ void xcd_barrier(const XcdBarrier& b) {
;     ...
;     }
;     __syncthreads();
.LBB0_562:
	s_or_b64 exec, exec, s[0:1]
	s_waitcnt lgkmcnt(0)
	s_barrier
	s_nop 0
	s_nop 0
	s_nop 0
